# also: decode attention P*V loop unrolled with the cache_v loads of two key groups in flight (was one dependent round trip per key in the copying waves)
# speedup vs baseline: 1.0391x; 1.0075x over previous
.LBB0_2684:
	s_or_b64 exec, exec, s[22:23]
	s_and_b32 s19, s30, 3
	s_lshl_b32 s19, s19, 8
	s_lshl_b64 s[20:21], s[20:21], 17
	s_or_b32 s22, s20, s19
	s_mov_b32 s23, s21
	v_lshl_add_u64 v[12:13], v[8:9], 0, s[22:23]
	v_lshl_add_u64 v[14:15], v[10:11], 0, s[22:23]
	v_mov_b32_e32 v32, 0
	s_mov_b64 s[22:23], 0
	v_mov_b32_e32 v33, v30
	v_mov_b32_e32 v34, v4
	s_waitcnt lgkmcnt(0)
	s_barrier
	s_mov_b32 s24, 0x1000
	s_mov_b32 s25, 0
	v_mov_b64_e32 v[206:207], v[12:13]
	v_mov_b64_e32 v[208:209], v[14:15]
	s_cmp_eq_u64 s[14:15], 0
	s_cbranch_scc1 .Ladec_nost
	global_load_dword v210, v[206:207], off offset:0
	global_load_dword v211, v[206:207], off offset:1024
	global_load_dword v212, v[206:207], off offset:2048
	global_load_dword v213, v[206:207], off offset:3072
	v_lshl_add_u64 v[206:207], v[206:207], 0, s[24:25]
	global_load_dword v214, v[206:207], off offset:0
	global_load_dword v215, v[206:207], off offset:1024
	global_load_dword v216, v[206:207], off offset:2048
	global_load_dword v217, v[206:207], off offset:3072
	v_lshl_add_u64 v[206:207], v[206:207], 0, s[24:25]
	ds_read_b32 v222, v33 offset:0
	ds_read_b32 v223, v33 offset:4
	ds_read_b32 v224, v33 offset:8
	ds_read_b32 v225, v33 offset:12
	ds_read_b32 v226, v33 offset:16
	ds_read_b32 v227, v33 offset:20
	ds_read_b32 v228, v33 offset:24
	ds_read_b32 v229, v33 offset:28
	s_waitcnt vmcnt(4) lgkmcnt(4)
	v_fmac_f32_e32 v32, v210, v222
	v_fmac_f32_e32 v32, v211, v223
	v_fmac_f32_e32 v32, v212, v224
	v_fmac_f32_e32 v32, v213, v225
	v_cmp_lt_i32_e32 vcc, 0, v34
	s_and_saveexec_b64 s[26:27], vcc
	s_cbranch_execz .Ladec_k0
	global_store_dword v[208:209], v210, off offset:-2048
.Ladec_k0:
	s_or_b64 exec, exec, s[26:27]
	global_store_dword v[208:209], v211, off offset:-1024
	global_store_dword v[208:209], v212, off offset:0
	global_store_dword v[208:209], v213, off offset:1024
	v_lshl_add_u64 v[208:209], v[208:209], 0, s[24:25]
	global_load_dword v218, v[206:207], off offset:0
	global_load_dword v219, v[206:207], off offset:1024
	global_load_dword v220, v[206:207], off offset:2048
	global_load_dword v221, v[206:207], off offset:3072
	v_lshl_add_u64 v[206:207], v[206:207], 0, s[24:25]
	ds_read_b32 v222, v33 offset:32
	ds_read_b32 v223, v33 offset:36
	ds_read_b32 v224, v33 offset:40
	ds_read_b32 v225, v33 offset:44
	s_waitcnt vmcnt(7) lgkmcnt(4)
	v_fmac_f32_e32 v32, v214, v226
	v_fmac_f32_e32 v32, v215, v227
	v_fmac_f32_e32 v32, v216, v228
	v_fmac_f32_e32 v32, v217, v229
	global_store_dword v[208:209], v214, off offset:-2048
	global_store_dword v[208:209], v215, off offset:-1024
	global_store_dword v[208:209], v216, off offset:0
	global_store_dword v[208:209], v217, off offset:1024
	v_lshl_add_u64 v[208:209], v[208:209], 0, s[24:25]
	global_load_dword v210, v[206:207], off offset:0
	global_load_dword v211, v[206:207], off offset:1024
	global_load_dword v212, v[206:207], off offset:2048
	global_load_dword v213, v[206:207], off offset:3072
	v_lshl_add_u64 v[206:207], v[206:207], 0, s[24:25]
	ds_read_b32 v226, v33 offset:48
	ds_read_b32 v227, v33 offset:52
	ds_read_b32 v228, v33 offset:56
	ds_read_b32 v229, v33 offset:60
	s_waitcnt vmcnt(8) lgkmcnt(4)
	v_fmac_f32_e32 v32, v218, v222
	v_fmac_f32_e32 v32, v219, v223
	v_fmac_f32_e32 v32, v220, v224
	v_fmac_f32_e32 v32, v221, v225
	global_store_dword v[208:209], v218, off offset:-2048
	global_store_dword v[208:209], v219, off offset:-1024
	global_store_dword v[208:209], v220, off offset:0
	global_store_dword v[208:209], v221, off offset:1024
	v_lshl_add_u64 v[208:209], v[208:209], 0, s[24:25]
	global_load_dword v214, v[206:207], off offset:0
	global_load_dword v215, v[206:207], off offset:1024
	global_load_dword v216, v[206:207], off offset:2048
	global_load_dword v217, v[206:207], off offset:3072
	v_lshl_add_u64 v[206:207], v[206:207], 0, s[24:25]
	ds_read_b32 v222, v33 offset:64
	ds_read_b32 v223, v33 offset:68
	ds_read_b32 v224, v33 offset:72
	ds_read_b32 v225, v33 offset:76
	s_waitcnt vmcnt(8) lgkmcnt(4)
	v_fmac_f32_e32 v32, v210, v226
	v_fmac_f32_e32 v32, v211, v227
	v_fmac_f32_e32 v32, v212, v228
	v_fmac_f32_e32 v32, v213, v229
	global_store_dword v[208:209], v210, off offset:-2048
	global_store_dword v[208:209], v211, off offset:-1024
	global_store_dword v[208:209], v212, off offset:0
	global_store_dword v[208:209], v213, off offset:1024
	v_lshl_add_u64 v[208:209], v[208:209], 0, s[24:25]
	global_load_dword v218, v[206:207], off offset:0
	global_load_dword v219, v[206:207], off offset:1024
	global_load_dword v220, v[206:207], off offset:2048
	global_load_dword v221, v[206:207], off offset:3072
	v_lshl_add_u64 v[206:207], v[206:207], 0, s[24:25]
	ds_read_b32 v226, v33 offset:80
	ds_read_b32 v227, v33 offset:84
	ds_read_b32 v228, v33 offset:88
	ds_read_b32 v229, v33 offset:92
	s_waitcnt vmcnt(8) lgkmcnt(4)
	v_fmac_f32_e32 v32, v214, v222
	v_fmac_f32_e32 v32, v215, v223
	v_fmac_f32_e32 v32, v216, v224
	v_fmac_f32_e32 v32, v217, v225
	global_store_dword v[208:209], v214, off offset:-2048
	global_store_dword v[208:209], v215, off offset:-1024
	global_store_dword v[208:209], v216, off offset:0
	global_store_dword v[208:209], v217, off offset:1024
	v_lshl_add_u64 v[208:209], v[208:209], 0, s[24:25]
	global_load_dword v210, v[206:207], off offset:0
	global_load_dword v211, v[206:207], off offset:1024
	global_load_dword v212, v[206:207], off offset:2048
	global_load_dword v213, v[206:207], off offset:3072
	v_lshl_add_u64 v[206:207], v[206:207], 0, s[24:25]
	ds_read_b32 v222, v33 offset:96
	ds_read_b32 v223, v33 offset:100
	ds_read_b32 v224, v33 offset:104
	ds_read_b32 v225, v33 offset:108
	s_waitcnt vmcnt(8) lgkmcnt(4)
	v_fmac_f32_e32 v32, v218, v226
	v_fmac_f32_e32 v32, v219, v227
	v_fmac_f32_e32 v32, v220, v228
	v_fmac_f32_e32 v32, v221, v229
	global_store_dword v[208:209], v218, off offset:-2048
	global_store_dword v[208:209], v219, off offset:-1024
	global_store_dword v[208:209], v220, off offset:0
	global_store_dword v[208:209], v221, off offset:1024
	v_lshl_add_u64 v[208:209], v[208:209], 0, s[24:25]
	global_load_dword v214, v[206:207], off offset:0
	global_load_dword v215, v[206:207], off offset:1024
	global_load_dword v216, v[206:207], off offset:2048
	global_load_dword v217, v[206:207], off offset:3072
	v_lshl_add_u64 v[206:207], v[206:207], 0, s[24:25]
	ds_read_b32 v226, v33 offset:112
	ds_read_b32 v227, v33 offset:116
	ds_read_b32 v228, v33 offset:120
	ds_read_b32 v229, v33 offset:124
	s_waitcnt vmcnt(8) lgkmcnt(4)
	v_fmac_f32_e32 v32, v210, v222
	v_fmac_f32_e32 v32, v211, v223
	v_fmac_f32_e32 v32, v212, v224
	v_fmac_f32_e32 v32, v213, v225
	global_store_dword v[208:209], v210, off offset:-2048
	global_store_dword v[208:209], v211, off offset:-1024
	global_store_dword v[208:209], v212, off offset:0
	global_store_dword v[208:209], v213, off offset:1024
	v_lshl_add_u64 v[208:209], v[208:209], 0, s[24:25]
	global_load_dword v218, v[206:207], off offset:0
	global_load_dword v219, v[206:207], off offset:1024
	global_load_dword v220, v[206:207], off offset:2048
	global_load_dword v221, v[206:207], off offset:3072
	v_lshl_add_u64 v[206:207], v[206:207], 0, s[24:25]
	ds_read_b32 v222, v33 offset:128
	ds_read_b32 v223, v33 offset:132
	ds_read_b32 v224, v33 offset:136
	ds_read_b32 v225, v33 offset:140
	s_waitcnt vmcnt(8) lgkmcnt(4)
	v_fmac_f32_e32 v32, v214, v226
	v_fmac_f32_e32 v32, v215, v227
	v_fmac_f32_e32 v32, v216, v228
	v_fmac_f32_e32 v32, v217, v229
	global_store_dword v[208:209], v214, off offset:-2048
	global_store_dword v[208:209], v215, off offset:-1024
	global_store_dword v[208:209], v216, off offset:0
	global_store_dword v[208:209], v217, off offset:1024
	v_lshl_add_u64 v[208:209], v[208:209], 0, s[24:25]
	global_load_dword v210, v[206:207], off offset:0
	global_load_dword v211, v[206:207], off offset:1024
	global_load_dword v212, v[206:207], off offset:2048
	global_load_dword v213, v[206:207], off offset:3072
	v_lshl_add_u64 v[206:207], v[206:207], 0, s[24:25]
	ds_read_b32 v226, v33 offset:144
	ds_read_b32 v227, v33 offset:148
	ds_read_b32 v228, v33 offset:152
	ds_read_b32 v229, v33 offset:156
	s_waitcnt vmcnt(8) lgkmcnt(4)
	v_fmac_f32_e32 v32, v218, v222
	v_fmac_f32_e32 v32, v219, v223
	v_fmac_f32_e32 v32, v220, v224
	v_fmac_f32_e32 v32, v221, v225
	global_store_dword v[208:209], v218, off offset:-2048
	global_store_dword v[208:209], v219, off offset:-1024
	global_store_dword v[208:209], v220, off offset:0
	global_store_dword v[208:209], v221, off offset:1024
	v_lshl_add_u64 v[208:209], v[208:209], 0, s[24:25]
	global_load_dword v214, v[206:207], off offset:0
	global_load_dword v215, v[206:207], off offset:1024
	global_load_dword v216, v[206:207], off offset:2048
	global_load_dword v217, v[206:207], off offset:3072
	v_lshl_add_u64 v[206:207], v[206:207], 0, s[24:25]
	ds_read_b32 v222, v33 offset:160
	ds_read_b32 v223, v33 offset:164
	ds_read_b32 v224, v33 offset:168
	ds_read_b32 v225, v33 offset:172
	s_waitcnt vmcnt(8) lgkmcnt(4)
	v_fmac_f32_e32 v32, v210, v226
	v_fmac_f32_e32 v32, v211, v227
	v_fmac_f32_e32 v32, v212, v228
	v_fmac_f32_e32 v32, v213, v229
	global_store_dword v[208:209], v210, off offset:-2048
	global_store_dword v[208:209], v211, off offset:-1024
	global_store_dword v[208:209], v212, off offset:0
	global_store_dword v[208:209], v213, off offset:1024
	v_lshl_add_u64 v[208:209], v[208:209], 0, s[24:25]
	global_load_dword v218, v[206:207], off offset:0
	global_load_dword v219, v[206:207], off offset:1024
	global_load_dword v220, v[206:207], off offset:2048
	global_load_dword v221, v[206:207], off offset:3072
	v_lshl_add_u64 v[206:207], v[206:207], 0, s[24:25]
	ds_read_b32 v226, v33 offset:176
	ds_read_b32 v227, v33 offset:180
	ds_read_b32 v228, v33 offset:184
	ds_read_b32 v229, v33 offset:188
	s_waitcnt vmcnt(8) lgkmcnt(4)
	v_fmac_f32_e32 v32, v214, v222
	v_fmac_f32_e32 v32, v215, v223
	v_fmac_f32_e32 v32, v216, v224
	v_fmac_f32_e32 v32, v217, v225
	global_store_dword v[208:209], v214, off offset:-2048
	global_store_dword v[208:209], v215, off offset:-1024
	global_store_dword v[208:209], v216, off offset:0
	global_store_dword v[208:209], v217, off offset:1024
	v_lshl_add_u64 v[208:209], v[208:209], 0, s[24:25]
	global_load_dword v210, v[206:207], off offset:0
	global_load_dword v211, v[206:207], off offset:1024
	global_load_dword v212, v[206:207], off offset:2048
	global_load_dword v213, v[206:207], off offset:3072
	v_lshl_add_u64 v[206:207], v[206:207], 0, s[24:25]
	ds_read_b32 v222, v33 offset:192
	ds_read_b32 v223, v33 offset:196
	ds_read_b32 v224, v33 offset:200
	ds_read_b32 v225, v33 offset:204
	s_waitcnt vmcnt(8) lgkmcnt(4)
	v_fmac_f32_e32 v32, v218, v226
	v_fmac_f32_e32 v32, v219, v227
	v_fmac_f32_e32 v32, v220, v228
	v_fmac_f32_e32 v32, v221, v229
	global_store_dword v[208:209], v218, off offset:-2048
	global_store_dword v[208:209], v219, off offset:-1024
	global_store_dword v[208:209], v220, off offset:0
	global_store_dword v[208:209], v221, off offset:1024
	v_lshl_add_u64 v[208:209], v[208:209], 0, s[24:25]
	global_load_dword v214, v[206:207], off offset:0
	global_load_dword v215, v[206:207], off offset:1024
	global_load_dword v216, v[206:207], off offset:2048
	global_load_dword v217, v[206:207], off offset:3072
	v_lshl_add_u64 v[206:207], v[206:207], 0, s[24:25]
	ds_read_b32 v226, v33 offset:208
	ds_read_b32 v227, v33 offset:212
	ds_read_b32 v228, v33 offset:216
	ds_read_b32 v229, v33 offset:220
	s_waitcnt vmcnt(8) lgkmcnt(4)
	v_fmac_f32_e32 v32, v210, v222
	v_fmac_f32_e32 v32, v211, v223
	v_fmac_f32_e32 v32, v212, v224
	v_fmac_f32_e32 v32, v213, v225
	global_store_dword v[208:209], v210, off offset:-2048
	global_store_dword v[208:209], v211, off offset:-1024
	global_store_dword v[208:209], v212, off offset:0
	global_store_dword v[208:209], v213, off offset:1024
	v_lshl_add_u64 v[208:209], v[208:209], 0, s[24:25]
	global_load_dword v218, v[206:207], off offset:0
	global_load_dword v219, v[206:207], off offset:1024
	global_load_dword v220, v[206:207], off offset:2048
	global_load_dword v221, v[206:207], off offset:3072
	v_lshl_add_u64 v[206:207], v[206:207], 0, s[24:25]
	ds_read_b32 v222, v33 offset:224
	ds_read_b32 v223, v33 offset:228
	ds_read_b32 v224, v33 offset:232
	ds_read_b32 v225, v33 offset:236
	s_waitcnt vmcnt(8) lgkmcnt(4)
	v_fmac_f32_e32 v32, v214, v226
	v_fmac_f32_e32 v32, v215, v227
	v_fmac_f32_e32 v32, v216, v228
	v_fmac_f32_e32 v32, v217, v229
	global_store_dword v[208:209], v214, off offset:-2048
	global_store_dword v[208:209], v215, off offset:-1024
	global_store_dword v[208:209], v216, off offset:0
	global_store_dword v[208:209], v217, off offset:1024
	v_lshl_add_u64 v[208:209], v[208:209], 0, s[24:25]
	global_load_dword v210, v[206:207], off offset:0
	global_load_dword v211, v[206:207], off offset:1024
	global_load_dword v212, v[206:207], off offset:2048
	global_load_dword v213, v[206:207], off offset:3072
	v_lshl_add_u64 v[206:207], v[206:207], 0, s[24:25]
	ds_read_b32 v226, v33 offset:240
	ds_read_b32 v227, v33 offset:244
	ds_read_b32 v228, v33 offset:248
	ds_read_b32 v229, v33 offset:252
	s_waitcnt vmcnt(8) lgkmcnt(4)
	v_fmac_f32_e32 v32, v218, v222
	v_fmac_f32_e32 v32, v219, v223
	v_fmac_f32_e32 v32, v220, v224
	v_fmac_f32_e32 v32, v221, v225
	global_store_dword v[208:209], v218, off offset:-2048
	global_store_dword v[208:209], v219, off offset:-1024
	global_store_dword v[208:209], v220, off offset:0
	global_store_dword v[208:209], v221, off offset:1024
	v_lshl_add_u64 v[208:209], v[208:209], 0, s[24:25]
	s_waitcnt vmcnt(4) lgkmcnt(0)
	v_fmac_f32_e32 v32, v210, v226
	v_fmac_f32_e32 v32, v211, v227
	v_fmac_f32_e32 v32, v212, v228
	v_fmac_f32_e32 v32, v213, v229
	global_store_dword v[208:209], v210, off offset:-2048
	global_store_dword v[208:209], v211, off offset:-1024
	global_store_dword v[208:209], v212, off offset:0
	global_store_dword v[208:209], v213, off offset:1024
	v_lshl_add_u64 v[208:209], v[208:209], 0, s[24:25]
	s_branch .LBB0_2694
.Ladec_nost:
	global_load_dword v210, v[206:207], off offset:0
	global_load_dword v211, v[206:207], off offset:1024
	global_load_dword v212, v[206:207], off offset:2048
	global_load_dword v213, v[206:207], off offset:3072
	v_lshl_add_u64 v[206:207], v[206:207], 0, s[24:25]
	global_load_dword v214, v[206:207], off offset:0
	global_load_dword v215, v[206:207], off offset:1024
	global_load_dword v216, v[206:207], off offset:2048
	global_load_dword v217, v[206:207], off offset:3072
	v_lshl_add_u64 v[206:207], v[206:207], 0, s[24:25]
	ds_read_b32 v222, v33 offset:0
	ds_read_b32 v223, v33 offset:4
	ds_read_b32 v224, v33 offset:8
	ds_read_b32 v225, v33 offset:12
	ds_read_b32 v226, v33 offset:16
	ds_read_b32 v227, v33 offset:20
	ds_read_b32 v228, v33 offset:24
	ds_read_b32 v229, v33 offset:28
	s_waitcnt vmcnt(4) lgkmcnt(4)
	v_fmac_f32_e32 v32, v210, v222
	v_fmac_f32_e32 v32, v211, v223
	v_fmac_f32_e32 v32, v212, v224
	v_fmac_f32_e32 v32, v213, v225
	global_load_dword v218, v[206:207], off offset:0
	global_load_dword v219, v[206:207], off offset:1024
	global_load_dword v220, v[206:207], off offset:2048
	global_load_dword v221, v[206:207], off offset:3072
	v_lshl_add_u64 v[206:207], v[206:207], 0, s[24:25]
	ds_read_b32 v222, v33 offset:32
	ds_read_b32 v223, v33 offset:36
	ds_read_b32 v224, v33 offset:40
	ds_read_b32 v225, v33 offset:44
	s_waitcnt vmcnt(4) lgkmcnt(4)
	v_fmac_f32_e32 v32, v214, v226
	v_fmac_f32_e32 v32, v215, v227
	v_fmac_f32_e32 v32, v216, v228
	v_fmac_f32_e32 v32, v217, v229
	global_load_dword v210, v[206:207], off offset:0
	global_load_dword v211, v[206:207], off offset:1024
	global_load_dword v212, v[206:207], off offset:2048
	global_load_dword v213, v[206:207], off offset:3072
	v_lshl_add_u64 v[206:207], v[206:207], 0, s[24:25]
	ds_read_b32 v226, v33 offset:48
	ds_read_b32 v227, v33 offset:52
	ds_read_b32 v228, v33 offset:56
	ds_read_b32 v229, v33 offset:60
	s_waitcnt vmcnt(4) lgkmcnt(4)
	v_fmac_f32_e32 v32, v218, v222
	v_fmac_f32_e32 v32, v219, v223
	v_fmac_f32_e32 v32, v220, v224
	v_fmac_f32_e32 v32, v221, v225
	global_load_dword v214, v[206:207], off offset:0
	global_load_dword v215, v[206:207], off offset:1024
	global_load_dword v216, v[206:207], off offset:2048
	global_load_dword v217, v[206:207], off offset:3072
	v_lshl_add_u64 v[206:207], v[206:207], 0, s[24:25]
	ds_read_b32 v222, v33 offset:64
	ds_read_b32 v223, v33 offset:68
	ds_read_b32 v224, v33 offset:72
	ds_read_b32 v225, v33 offset:76
	s_waitcnt vmcnt(4) lgkmcnt(4)
	v_fmac_f32_e32 v32, v210, v226
	v_fmac_f32_e32 v32, v211, v227
	v_fmac_f32_e32 v32, v212, v228
	v_fmac_f32_e32 v32, v213, v229
	global_load_dword v218, v[206:207], off offset:0
	global_load_dword v219, v[206:207], off offset:1024
	global_load_dword v220, v[206:207], off offset:2048
	global_load_dword v221, v[206:207], off offset:3072
	v_lshl_add_u64 v[206:207], v[206:207], 0, s[24:25]
	ds_read_b32 v226, v33 offset:80
	ds_read_b32 v227, v33 offset:84
	ds_read_b32 v228, v33 offset:88
	ds_read_b32 v229, v33 offset:92
	s_waitcnt vmcnt(4) lgkmcnt(4)
	v_fmac_f32_e32 v32, v214, v222
	v_fmac_f32_e32 v32, v215, v223
	v_fmac_f32_e32 v32, v216, v224
	v_fmac_f32_e32 v32, v217, v225
	global_load_dword v210, v[206:207], off offset:0
	global_load_dword v211, v[206:207], off offset:1024
	global_load_dword v212, v[206:207], off offset:2048
	global_load_dword v213, v[206:207], off offset:3072
	v_lshl_add_u64 v[206:207], v[206:207], 0, s[24:25]
	ds_read_b32 v222, v33 offset:96
	ds_read_b32 v223, v33 offset:100
	ds_read_b32 v224, v33 offset:104
	ds_read_b32 v225, v33 offset:108
	s_waitcnt vmcnt(4) lgkmcnt(4)
	v_fmac_f32_e32 v32, v218, v226
	v_fmac_f32_e32 v32, v219, v227
	v_fmac_f32_e32 v32, v220, v228
	v_fmac_f32_e32 v32, v221, v229
	global_load_dword v214, v[206:207], off offset:0
	global_load_dword v215, v[206:207], off offset:1024
	global_load_dword v216, v[206:207], off offset:2048
	global_load_dword v217, v[206:207], off offset:3072
	v_lshl_add_u64 v[206:207], v[206:207], 0, s[24:25]
	ds_read_b32 v226, v33 offset:112
	ds_read_b32 v227, v33 offset:116
	ds_read_b32 v228, v33 offset:120
	ds_read_b32 v229, v33 offset:124
	s_waitcnt vmcnt(4) lgkmcnt(4)
	v_fmac_f32_e32 v32, v210, v222
	v_fmac_f32_e32 v32, v211, v223
	v_fmac_f32_e32 v32, v212, v224
	v_fmac_f32_e32 v32, v213, v225
	global_load_dword v218, v[206:207], off offset:0
	global_load_dword v219, v[206:207], off offset:1024
	global_load_dword v220, v[206:207], off offset:2048
	global_load_dword v221, v[206:207], off offset:3072
	v_lshl_add_u64 v[206:207], v[206:207], 0, s[24:25]
	ds_read_b32 v222, v33 offset:128
	ds_read_b32 v223, v33 offset:132
	ds_read_b32 v224, v33 offset:136
	ds_read_b32 v225, v33 offset:140
	s_waitcnt vmcnt(4) lgkmcnt(4)
	v_fmac_f32_e32 v32, v214, v226
	v_fmac_f32_e32 v32, v215, v227
	v_fmac_f32_e32 v32, v216, v228
	v_fmac_f32_e32 v32, v217, v229
	global_load_dword v210, v[206:207], off offset:0
	global_load_dword v211, v[206:207], off offset:1024
	global_load_dword v212, v[206:207], off offset:2048
	global_load_dword v213, v[206:207], off offset:3072
	v_lshl_add_u64 v[206:207], v[206:207], 0, s[24:25]
	ds_read_b32 v226, v33 offset:144
	ds_read_b32 v227, v33 offset:148
	ds_read_b32 v228, v33 offset:152
	ds_read_b32 v229, v33 offset:156
	s_waitcnt vmcnt(4) lgkmcnt(4)
	v_fmac_f32_e32 v32, v218, v222
	v_fmac_f32_e32 v32, v219, v223
	v_fmac_f32_e32 v32, v220, v224
	v_fmac_f32_e32 v32, v221, v225
	global_load_dword v214, v[206:207], off offset:0
	global_load_dword v215, v[206:207], off offset:1024
	global_load_dword v216, v[206:207], off offset:2048
	global_load_dword v217, v[206:207], off offset:3072
	v_lshl_add_u64 v[206:207], v[206:207], 0, s[24:25]
	ds_read_b32 v222, v33 offset:160
	ds_read_b32 v223, v33 offset:164
	ds_read_b32 v224, v33 offset:168
	ds_read_b32 v225, v33 offset:172
	s_waitcnt vmcnt(4) lgkmcnt(4)
	v_fmac_f32_e32 v32, v210, v226
	v_fmac_f32_e32 v32, v211, v227
	v_fmac_f32_e32 v32, v212, v228
	v_fmac_f32_e32 v32, v213, v229
	global_load_dword v218, v[206:207], off offset:0
	global_load_dword v219, v[206:207], off offset:1024
	global_load_dword v220, v[206:207], off offset:2048
	global_load_dword v221, v[206:207], off offset:3072
	v_lshl_add_u64 v[206:207], v[206:207], 0, s[24:25]
	ds_read_b32 v226, v33 offset:176
	ds_read_b32 v227, v33 offset:180
	ds_read_b32 v228, v33 offset:184
	ds_read_b32 v229, v33 offset:188
	s_waitcnt vmcnt(4) lgkmcnt(4)
	v_fmac_f32_e32 v32, v214, v222
	v_fmac_f32_e32 v32, v215, v223
	v_fmac_f32_e32 v32, v216, v224
	v_fmac_f32_e32 v32, v217, v225
	global_load_dword v210, v[206:207], off offset:0
	global_load_dword v211, v[206:207], off offset:1024
	global_load_dword v212, v[206:207], off offset:2048
	global_load_dword v213, v[206:207], off offset:3072
	v_lshl_add_u64 v[206:207], v[206:207], 0, s[24:25]
	ds_read_b32 v222, v33 offset:192
	ds_read_b32 v223, v33 offset:196
	ds_read_b32 v224, v33 offset:200
	ds_read_b32 v225, v33 offset:204
	s_waitcnt vmcnt(4) lgkmcnt(4)
	v_fmac_f32_e32 v32, v218, v226
	v_fmac_f32_e32 v32, v219, v227
	v_fmac_f32_e32 v32, v220, v228
	v_fmac_f32_e32 v32, v221, v229
	global_load_dword v214, v[206:207], off offset:0
	global_load_dword v215, v[206:207], off offset:1024
	global_load_dword v216, v[206:207], off offset:2048
	global_load_dword v217, v[206:207], off offset:3072
	v_lshl_add_u64 v[206:207], v[206:207], 0, s[24:25]
	ds_read_b32 v226, v33 offset:208
	ds_read_b32 v227, v33 offset:212
	ds_read_b32 v228, v33 offset:216
	ds_read_b32 v229, v33 offset:220
	s_waitcnt vmcnt(4) lgkmcnt(4)
	v_fmac_f32_e32 v32, v210, v222
	v_fmac_f32_e32 v32, v211, v223
	v_fmac_f32_e32 v32, v212, v224
	v_fmac_f32_e32 v32, v213, v225
	global_load_dword v218, v[206:207], off offset:0
	global_load_dword v219, v[206:207], off offset:1024
	global_load_dword v220, v[206:207], off offset:2048
	global_load_dword v221, v[206:207], off offset:3072
	v_lshl_add_u64 v[206:207], v[206:207], 0, s[24:25]
	ds_read_b32 v222, v33 offset:224
	ds_read_b32 v223, v33 offset:228
	ds_read_b32 v224, v33 offset:232
	ds_read_b32 v225, v33 offset:236
	s_waitcnt vmcnt(4) lgkmcnt(4)
	v_fmac_f32_e32 v32, v214, v226
	v_fmac_f32_e32 v32, v215, v227
	v_fmac_f32_e32 v32, v216, v228
	v_fmac_f32_e32 v32, v217, v229
	global_load_dword v210, v[206:207], off offset:0
	global_load_dword v211, v[206:207], off offset:1024
	global_load_dword v212, v[206:207], off offset:2048
	global_load_dword v213, v[206:207], off offset:3072
	v_lshl_add_u64 v[206:207], v[206:207], 0, s[24:25]
	ds_read_b32 v226, v33 offset:240
	ds_read_b32 v227, v33 offset:244
	ds_read_b32 v228, v33 offset:248
	ds_read_b32 v229, v33 offset:252
	s_waitcnt vmcnt(4) lgkmcnt(4)
	v_fmac_f32_e32 v32, v218, v222
	v_fmac_f32_e32 v32, v219, v223
	v_fmac_f32_e32 v32, v220, v224
	v_fmac_f32_e32 v32, v221, v225
	s_waitcnt vmcnt(0) lgkmcnt(0)
	v_fmac_f32_e32 v32, v210, v226
	v_fmac_f32_e32 v32, v211, v227
	v_fmac_f32_e32 v32, v212, v228
	v_fmac_f32_e32 v32, v213, v229
